# P0: the only third work item (workgroup 0) handed to workgroup 255
# speedup vs baseline: 1.0724x; 1.0002x over previous
.LBB0_164:
	v_mov_b32 v198, v0
	s_lshl_b32 s33, s42, 7
	v_and_b32_e32 v202, 15, v198
	v_lshlrev_b32_e32 v197, 3, v202
	v_or_b32_e32 v194, s33, v197
	v_ashrrev_i32_e32 v195, 31, v194
	v_lshlrev_b64 v[42:43], 2, v[194:195]
	v_readlane_b32 s0, v254, 19
	v_lshl_add_u64 v[6:7], s[86:87], 0, v[42:43]
	v_readlane_b32 s1, v254, 20
	global_load_dwordx4 v[2:5], v[6:7], off offset:16
	global_load_dwordx4 v[18:21], v[6:7], off
	v_lshl_add_u64 v[6:7], s[0:1], 0, v[42:43]
	v_readlane_b32 s0, v254, 21
	v_readlane_b32 s1, v254, 22
	global_load_dwordx4 v[58:61], v[6:7], off offset:16
	global_load_dwordx4 v[62:65], v[6:7], off
	v_lshl_add_u64 v[10:11], s[0:1], 0, v[42:43]
	v_readlane_b32 s0, v254, 23
	v_readlane_b32 s1, v254, 24
	global_load_dwordx4 v[6:9], v[10:11], off offset:16
	global_load_dwordx4 v[22:25], v[10:11], off
	v_lshl_add_u64 v[10:11], s[0:1], 0, v[42:43]
	v_readlane_b32 s0, v254, 25
	v_readlane_b32 s1, v254, 26
	global_load_dwordx4 v[46:49], v[10:11], off offset:16
	global_load_dwordx4 v[34:37], v[10:11], off
	v_lshl_add_u64 v[14:15], s[0:1], 0, v[42:43]
	v_readlane_b32 s0, v254, 27
	v_readlane_b32 s1, v254, 28
	global_load_dwordx4 v[10:13], v[14:15], off offset:16
	global_load_dwordx4 v[26:29], v[14:15], off
	v_lshl_add_u64 v[14:15], s[0:1], 0, v[42:43]
	v_readlane_b32 s0, v254, 29
	v_readlane_b32 s1, v254, 30
	v_lshl_add_u64 v[30:31], s[88:89], 0, v[42:43]
	global_load_dwordx4 v[50:53], v[14:15], off offset:16
	global_load_dwordx4 v[38:41], v[14:15], off
	v_lshl_add_u64 v[42:43], s[0:1], 0, v[42:43]
	global_load_dwordx4 v[14:17], v[30:31], off offset:16
	s_nop 0
	global_load_dwordx4 v[30:33], v[30:31], off
	s_nop 0
	global_load_dwordx4 v[54:57], v[42:43], off offset:16
	s_nop 0
	global_load_dwordx4 v[42:45], v[42:43], off
	v_lshrrev_b32_e32 v199, 2, v198
	s_mov_b32 s0, 0xfffffc0
	v_and_or_b32 v199, v199, s0, v202
	s_movk_i32 s0, 0x210
	v_mul_lo_u32 v199, v199, s0
	v_cvt_pk_bf16_f32 v182, v182, v183
	v_cvt_pk_bf16_f32 v183, v184, v185
	v_lshrrev_b32_e32 v184, 1, v198
	v_add_u32_e32 v199, 0, v199
	v_and_b32_e32 v184, 24, v184
	v_and_b32_e32 v185, 0xc0, v198
	v_add3_u32 v184, v199, v185, v184
	v_cvt_pk_bf16_f32 v122, v122, v123
	v_cvt_pk_bf16_f32 v123, v124, v125
	v_cvt_pk_bf16_f32 v114, v114, v115
	v_cvt_pk_bf16_f32 v115, v116, v117
	v_add_u32_e32 v124, 0x6000, v184
	v_cvt_pk_bf16_f32 v116, v130, v131
	ds_write2_b64 v124, v[122:123], v[114:115] offset0:96 offset1:100
	v_cvt_pk_bf16_f32 v114, v138, v139
	v_cvt_pk_bf16_f32 v115, v140, v141
	v_cvt_pk_bf16_f32 v117, v132, v133
	ds_write2_b64 v124, v[114:115], v[116:117] offset0:128 offset1:132
	v_add_u32_e32 v116, 0x10800, v184
	v_cvt_pk_bf16_f32 v86, v86, v87
	v_cvt_pk_bf16_f32 v87, v88, v89
	v_add_u32_e32 v88, 0x14a20, v184
	v_cvt_pk_bf16_f32 v114, v142, v143
	v_cvt_pk_bf16_f32 v115, v144, v145
	ds_write_b64 v116, v[114:115]
	v_add_u32_e32 v116, 0x10820, v184
	ds_write_b64 v88, v[86:87]
	v_cvt_pk_bf16_f32 v86, v90, v91
	v_add_u32_e32 v88, 0x14b00, v184
	v_cvt_pk_bf16_f32 v114, v126, v127
	v_cvt_pk_bf16_f32 v115, v128, v129
	ds_write_b64 v116, v[114:115]
	v_add_u32_e32 v116, 0x10900, v184
	v_cvt_pk_bf16_f32 v102, v102, v103
	v_cvt_pk_bf16_f32 v103, v104, v105
	v_add_u32_e32 v104, 0x12920, v184
	v_cvt_pk_bf16_f32 v87, v92, v93
	ds_write_b64 v88, v[86:87]
	v_cvt_pk_bf16_f32 v78, v78, v79
	v_cvt_pk_bf16_f32 v79, v80, v81
	v_add_u32_e32 v80, 0x16b00, v184
	v_cvt_pk_bf16_f32 v70, v70, v71
	v_cvt_pk_bf16_f32 v71, v72, v73
	v_add_u32_e32 v72, 0x16b20, v184
	v_cvt_pk_bf16_f32 v66, v66, v67
	v_cvt_pk_bf16_f32 v67, v68, v69
	v_add_u32_e32 v68, 0x16c20, v184
	v_ashrrev_i32_e32 v86, 4, v198
	s_movk_i32 s16, 0x1080
	v_cvt_pk_bf16_f32 v178, v178, v179
	v_cvt_pk_bf16_f32 v179, v180, v181
	v_cvt_pk_bf16_f32 v166, v166, v167
	v_cvt_pk_bf16_f32 v167, v168, v169
	v_cvt_pk_bf16_f32 v162, v162, v163
	v_cvt_pk_bf16_f32 v163, v164, v165
	v_add_u32_e32 v168, 0x2000, v184
	v_cvt_pk_bf16_f32 v150, v150, v151
	v_cvt_pk_bf16_f32 v151, v152, v153
	v_cvt_pk_bf16_f32 v146, v146, v147
	v_cvt_pk_bf16_f32 v147, v148, v149
	v_add_u32_e32 v152, 0x4000, v184
	v_cvt_pk_bf16_f32 v114, v134, v135
	v_cvt_pk_bf16_f32 v115, v136, v137
	ds_write_b64 v116, v[114:115]
	v_add_u32_e32 v116, 0x10920, v184
	v_cvt_pk_bf16_f32 v110, v110, v111
	v_cvt_pk_bf16_f32 v111, v112, v113
	v_add_u32_e32 v112, 0x12900, v184
	ds_write_b64 v104, v[102:103]
	v_add_u32_e32 v104, 0x12a00, v184
	v_cvt_pk_bf16_f32 v98, v98, v99
	v_cvt_pk_bf16_f32 v99, v100, v101
	v_add_u32_e32 v100, 0x12a20, v184
	v_cvt_pk_bf16_f32 v94, v94, v95
	v_cvt_pk_bf16_f32 v95, v96, v97
	v_add_u32_e32 v96, 0x14a00, v184
	v_cvt_pk_bf16_f32 v82, v82, v83
	v_cvt_pk_bf16_f32 v83, v84, v85
	v_add_u32_e32 v84, 0x14b20, v184
	ds_write_b64 v80, v[78:79]
	ds_write_b64 v72, v[70:71]
	v_add_u32_e32 v72, 0x16c00, v184
	ds_write_b64 v68, v[66:67]
	v_cmp_lt_i32_e32 vcc, 0, v86
	v_cmp_gt_i32_e64 s[0:1], 1, v86
	v_lshlrev_b32_e32 v80, 4, v202
	v_mul_lo_u32 v66, v86, s16
	ds_write2_b64 v184, v[182:183], v[178:179] offset1:4
	v_cvt_pk_bf16_f32 v178, v190, v191
	v_cvt_pk_bf16_f32 v179, v192, v193
	v_cvt_pk_bf16_f32 v180, v186, v187
	v_cvt_pk_bf16_f32 v181, v188, v189
	ds_write2_b64 v184, v[178:179], v[180:181] offset0:32 offset1:36
	ds_write2_b64 v168, v[166:167], v[162:163] offset0:32 offset1:36
	v_cvt_pk_bf16_f32 v162, v174, v175
	v_cvt_pk_bf16_f32 v163, v176, v177
	v_cvt_pk_bf16_f32 v164, v170, v171
	v_cvt_pk_bf16_f32 v165, v172, v173
	ds_write2_b64 v168, v[162:163], v[164:165] offset0:64 offset1:68
	ds_write2_b64 v152, v[150:151], v[146:147] offset0:64 offset1:68
	v_cvt_pk_bf16_f32 v146, v158, v159
	v_cvt_pk_bf16_f32 v147, v160, v161
	v_cvt_pk_bf16_f32 v148, v154, v155
	v_cvt_pk_bf16_f32 v149, v156, v157
	ds_write2_b64 v152, v[146:147], v[148:149] offset0:96 offset1:100
	v_cvt_pk_bf16_f32 v114, v118, v119
	v_cvt_pk_bf16_f32 v115, v120, v121
	ds_write_b64 v116, v[114:115]
	ds_write_b64 v112, v[110:111]
	v_cvt_pk_bf16_f32 v102, v106, v107
	v_cvt_pk_bf16_f32 v103, v108, v109
	ds_write_b64 v104, v[102:103]
	ds_write_b64 v100, v[98:99]
	ds_write_b64 v96, v[94:95]
	ds_write_b64 v84, v[82:83]
	v_cvt_pk_bf16_f32 v70, v74, v75
	v_cvt_pk_bf16_f32 v71, v76, v77
	ds_write_b64 v72, v[70:71]
	s_waitcnt vmcnt(0) lgkmcnt(0)
	s_barrier
	s_add_i32 s52, s42, 4
	s_cmp_lt_i32 s52, 22
	s_cbranch_scc0 .Lp5_pf_skip
	v_readlane_b32 s54, v255, 33
	v_readlane_b32 s55, v255, 34
	v_readlane_b32 s56, v255, 35
	v_readlane_b32 s57, v255, 36
	s_lshl_b32 s53, s36, 19
	s_add_u32 s54, s54, s53
	s_addc_u32 s55, s55, 0
	s_lshl_b32 s53, s52, 19
	s_add_u32 s56, s56, s53
	s_addc_u32 s57, s57, 0
	v_readfirstlane_b32 s53, v0
	s_nop 1
	s_cmp_lt_u32 s53, 0x100
	s_cselect_b32 s54, s54, s56
	s_cselect_b32 s55, s55, s57
	v_and_b32_e32 v222, 0xff, v0
	v_lshlrev_b32_e32 v222, 11, v222
	global_load_dword v250, v222, s[54:55]

.LBB0_421:
	s_load_dword s0, s[78:79], 0x0
	s_waitcnt lgkmcnt(0)
	s_add_i32 s2, s0, s2
	s_cmpk_lg_i32 s0, 0x100
	s_cbranch_scc1 .Lp0_item_norm
	s_cmpk_eq_i32 s2, 0x200
	s_cbranch_scc1 .LBB0_6
	s_cmpk_eq_i32 s2, 0x2ff
	s_cbranch_scc0 .Lp0_item_norm
	s_movk_i32 s2, 0x200
	s_branch .LBB0_422
.Lp0_item_norm:
	s_cmpk_gt_i32 s2, 0x200
	s_cbranch_scc1 .LBB0_6
